# the same static s_setprio 1, built for the other half: the workgroup that registered first on its CU
# baseline (speedup 1.0000x reference)
.LBB0_61:
	s_cmp_eq_u32 s17, 1
	s_cbranch_scc0 .Lbar_chk_done
	s_mov_b64 exec, 1
	v_readlane_b32 s4, v252, 4
	v_readlane_b32 s5, v252, 5
	v_mov_b32_e32 v3, 0x3400
	s_nop 3
	global_load_dwordx4 v[4:7], v3, s[4:5] sc1
	global_load_dwordx4 v[8:11], v3, s[4:5] offset:16 sc1
	s_mov_b32 s10, 0
	s_mov_b32 s11, 1
	s_waitcnt vmcnt(0)
	v_readfirstlane_b32 s6, v4
	s_bcnt1_i32_b32 s7, s6
	s_cmp_eq_u32 s7, 1
	s_cselect_b32 s11, s11, 0
	s_or_b32 s10, s10, s6
	v_readfirstlane_b32 s6, v5
	s_bcnt1_i32_b32 s7, s6
	s_cmp_eq_u32 s7, 1
	s_cselect_b32 s11, s11, 0
	s_or_b32 s10, s10, s6
	v_readfirstlane_b32 s6, v6
	s_bcnt1_i32_b32 s7, s6
	s_cmp_eq_u32 s7, 1
	s_cselect_b32 s11, s11, 0
	s_or_b32 s10, s10, s6
	v_readfirstlane_b32 s6, v7
	s_bcnt1_i32_b32 s7, s6
	s_cmp_eq_u32 s7, 1
	s_cselect_b32 s11, s11, 0
	s_or_b32 s10, s10, s6
	v_readfirstlane_b32 s6, v8
	s_bcnt1_i32_b32 s7, s6
	s_cmp_eq_u32 s7, 1
	s_cselect_b32 s11, s11, 0
	s_or_b32 s10, s10, s6
	v_readfirstlane_b32 s6, v9
	s_bcnt1_i32_b32 s7, s6
	s_cmp_eq_u32 s7, 1
	s_cselect_b32 s11, s11, 0
	s_or_b32 s10, s10, s6
	v_readfirstlane_b32 s6, v10
	s_bcnt1_i32_b32 s7, s6
	s_cmp_eq_u32 s7, 1
	s_cselect_b32 s11, s11, 0
	s_or_b32 s10, s10, s6
	v_readfirstlane_b32 s6, v11
	s_bcnt1_i32_b32 s7, s6
	s_cmp_eq_u32 s7, 1
	s_cselect_b32 s11, s11, 0
	s_or_b32 s10, s10, s6
	s_bcnt1_i32_b32 s7, s10
	s_cmp_eq_u32 s7, 8
	s_cselect_b32 s11, s11, 0
	v_readlane_b32 s6, v252, 2
	v_readlane_b32 s7, v252, 3
	s_load_dword s6, s[6:7], 0x0
	s_waitcnt lgkmcnt(0)
	s_and_b32 s6, s6, 63
	s_cmp_eq_u32 s6, 0
	s_cselect_b32 s11, s11, 0
	s_nop 0
	v_writelane_b32 v255, s11, 40
	s_mov_b64 exec, -1
	v_mov_b32_e32 v3, 0x12ff8
	ds_read_b32 v3, v3
	s_getreg_b32 s6, hwreg(HW_REG_XCC_ID, 0, 4)
	s_and_b32 s6, s6, 7
	s_lshl_b32 s6, s6, 8
	s_addk_i32 s6, 0x3500
	v_lshl_add_u32 v4, v198, 2, s6
	global_load_dword v4, v4, s[4:5] sc1
	s_getreg_b32 s7, hwreg(HW_REG_HW_ID, 8, 8)
	s_mov_b32 s100, 0
	s_mov_b32 s101, 0
	s_waitcnt vmcnt(0) lgkmcnt(0)
	v_readfirstlane_b32 s10, v3
	v_and_b32_e32 v5, 0xfdfdfdfd, v4
	v_cmp_ne_u32_e32 vcc, 0, v5
	s_cmp_lg_u64 vcc, 0
	s_cselect_b32 s11, 0, s11
	s_cmp_lt_u32 s10, 2
	s_cselect_b32 s11, s11, 0
	s_lshr_b32 s6, s7, 2
	s_lshl_b64 s[4:5], 1, s6
	s_sub_u32 s4, s4, 1
	s_subb_u32 s5, s5, 0
	v_readlane_b32 s6, v4, s6
	s_and_b32 s7, s7, 3
	s_lshl_b32 s7, s7, 3
	s_bfm_b32 s7, s7, 0
	s_and_b32 s6, s6, s7
	s_bcnt1_i32_b32 s101, s6
	v_bfe_u32 v5, v4, 1, 1
	v_cmp_ne_u32_e32 vcc, 0, v5
	s_bcnt1_i32_b64 s6, vcc
	s_add_u32 s100, s100, s6
	s_and_b64 vcc, vcc, s[4:5]
	s_bcnt1_i32_b64 s6, vcc
	s_add_u32 s101, s101, s6
	v_bfe_u32 v5, v4, 9, 1
	v_cmp_ne_u32_e32 vcc, 0, v5
	s_bcnt1_i32_b64 s6, vcc
	s_add_u32 s100, s100, s6
	s_and_b64 vcc, vcc, s[4:5]
	s_bcnt1_i32_b64 s6, vcc
	s_add_u32 s101, s101, s6
	v_bfe_u32 v5, v4, 17, 1
	v_cmp_ne_u32_e32 vcc, 0, v5
	s_bcnt1_i32_b64 s6, vcc
	s_add_u32 s100, s100, s6
	s_and_b64 vcc, vcc, s[4:5]
	s_bcnt1_i32_b64 s6, vcc
	s_add_u32 s101, s101, s6
	v_bfe_u32 v5, v4, 25, 1
	v_cmp_ne_u32_e32 vcc, 0, v5
	s_bcnt1_i32_b64 s6, vcc
	s_add_u32 s100, s100, s6
	s_and_b64 vcc, vcc, s[4:5]
	s_bcnt1_i32_b64 s6, vcc
	s_add_u32 s101, s101, s6
	s_cmp_eq_u32 s100, 32
	s_cselect_b32 s11, s11, 0
	s_lshl_b32 s10, s10, 8
	s_or_b32 s10, s10, s101
	s_cmp_eq_u32 s11, 1
	s_cselect_b32 s10, s10, -1
	s_nop 0
	v_writelane_b32 v255, s10, 49
	s_cmp_eq_u32 s10, -1
	s_cbranch_scc1 .Lbar_chk_done
	s_bitcmp1_b32 s10, 8
	s_cbranch_scc1 .Lbar_chk_done
	s_setprio 1
